# GEMM K-loop barrier hand-off trimmed: setprio raise moved before the pre-MFMA barrier, redundant lgkmcnt wait and mid-block setprio pair removed, setprio drop moved behind the post-MFMA barrier (on to
# speedup vs baseline: 1.0118x; 1.0118x over previous
; #define PG8_STAGE(bufoff, gbase, voff) do { _Pragma("unroll") for (int _i = 0; _i < 2; ++_i) \
;         __builtin_amdgcn_global_load_lds((const unsigned*)((const char*)(gbase) + (voff)[_i]), (PG8_LAS unsigned*)(lds + (bufoff) + ldsw + _i * 8192), 16, 0, 0); } while (0)
; #define PG8_LDA(dst, b, h) do { _Pragma("unroll") for (int m = 0; m < 4; ++m) _Pragma("unroll") for (int k = 0; k < 2; ++k) dst[m][k] = *(const PG8_LAS bf16x8*)(lds + PG8_SA(b, h) + aoff + m * 2048 + k * 1024); } while (0)
; #define PG8_LDB(dst, b, h) do { _Pragma("unroll") for (int n = 0; n < 2; ++n) _Pragma("unroll") for (int k = 0; k < 2; ++k) dst[n][k] = *(const PG8_LAS bf16x8*)(lds + PG8_SB(b, h) + boff + n * 2048 + k * 1024); } while (0)
; #define PG8_MMA(ai, bj, At, Bt) do { __builtin_amdgcn_s_setprio(1); _Pragma("unroll") for (int m = 0; m < 4; ++m) _Pragma("unroll") for (int n = 0; n < 2; ++n) _Pragma("unroll") for (int k = 0; k < 2; ++k) \
;         acc[ai][bj][m][n] = __builtin_amdgcn_mfma_f32_16x16x32_bf16(Bt[n][k], At[m][k], acc[ai][bj][m][n], 0, 0, 0); __builtin_amdgcn_s_setprio(0); } while (0)
; #define PG8_WAIT_V(n) asm volatile("s_waitcnt vmcnt(" #n ")" ::: "memory")
; template <class Epi, class Sched, bool ALIGN_EPI = false, bool SP2 = false>
; __device__ __forceinline__ void gemm_phase(PG8_LAS unsigned char* lds, const Gemm g, const Sched& S, const Epi& E) {
;     ...
;             PG8_LDB(B0, 0, 0); PG8_LDB(B1, 0, 1); PG8_SCHED; PG8_LDA(At, 0, 0); PG8_STAGE(PG8_SA(1, 1), a1 + hstep, voffA);
;             PG8_WAIT_V(8); PG8_WAIT_L(0); PG8_BAR; PG8_MMA(0, 0, At, B0); PG8_MMA(0, 1, At, B1); PG8_BAR; PG8_SCHED;
;             PG8_LDA(At, 0, 1); PG8_STAGE(PG8_SB(0, 0), b2, voffB); PG8_STAGE(PG8_SB(0, 1), b2 + hstep, voffB); PG8_STAGE(PG8_SA(0, 0), a2, voffA);
;             PG8_WAIT_V(8); PG8_WAIT_L(0); PG8_BAR; PG8_MMA(1, 0, At, B0); PG8_MMA(1, 1, At, B1); PG8_BAR; PG8_SCHED;
;             PG8_LDB(B0, 1, 0); PG8_LDB(B1, 1, 1); PG8_SCHED; PG8_LDA(At, 1, 0); PG8_STAGE(PG8_SA(0, 1), a2 + hstep, voffA);
;             PG8_WAIT_V(8); PG8_WAIT_L(0); PG8_BAR; PG8_MMA(0, 0, At, B0); PG8_MMA(0, 1, At, B1); PG8_BAR; PG8_SCHED;
;             PG8_LDA(At, 1, 1); PG8_STAGE(PG8_SB(1, 0), b3, voffB); PG8_STAGE(PG8_SB(1, 1), b3 + hstep, voffB); PG8_STAGE(PG8_SA(1, 0), a3, voffA);
;             PG8_WAIT_V(8); PG8_WAIT_L(0); PG8_BAR; PG8_MMA(1, 0, At, B0); PG8_MMA(1, 1, At, B1); PG8_BAR; PG8_SCHED;
.LBB0_56:
	s_add_i32 s2, s34, 2
	s_add_u32 s35, s28, s30
	s_addc_u32 s62, s29, s31
	s_add_u32 s63, s35, 0x100
	s_addc_u32 s35, s62, 0
	s_add_u32 s62, s60, s30
	s_addc_u32 s64, s61, s31
	s_add_i32 s65, 0, 0x10000
	s_cmp_eq_u32 s48, s34
	s_cselect_b32 s35, s1, s35
	s_cselect_b32 s34, s0, s63
	v_add_u32_e32 v0, s65, v188
	s_cselect_b32 s63, s27, s64
	s_cselect_b32 s62, s26, s62
	s_add_i32 s64, 0, 0x14000
	ds_read_b128 v[132:135], v0
	ds_read_b128 v[136:139], v0 offset:1024
	ds_read_b128 v[140:143], v0 offset:2048
	ds_read_b128 v[144:147], v0 offset:3072
	v_add_u32_e32 v0, s64, v188
	ds_read_b128 v[148:151], v0
	ds_read_b128 v[152:155], v0 offset:1024
	ds_read_b128 v[156:159], v0 offset:2048
	ds_read_b128 v[160:163], v0 offset:3072
	v_lshl_add_u64 v[2:3], v[204:205], 0, s[30:31]
	s_add_i32 m0, s43, 0xc000
	ds_read_b128 v[164:167], v235
	ds_read_b128 v[168:171], v235 offset:1024
	ds_read_b128 v[172:175], v235 offset:2048
	ds_read_b128 v[176:179], v235 offset:3072
	ds_read_b128 v[180:183], v235 offset:4096
	ds_read_b128 v[184:187], v235 offset:5120
	ds_read_b128 v[236:239], v235 offset:6144
	ds_read_b128 v[240:243], v235 offset:7168
	global_load_lds_dwordx4 v[2:3], off
	v_lshl_add_u64 v[2:3], v[206:207], 0, s[30:31]
	s_add_i32 m0, s43, 0xe000
	s_nop 0
	global_load_lds_dwordx4 v[2:3], off
	s_waitcnt vmcnt(8)
	s_waitcnt lgkmcnt(0)
	s_setprio 1
	s_barrier
	v_mfma_f32_16x16x32_bf16 v[116:119], v[132:135], v[164:167], v[116:119]
	v_mfma_f32_16x16x32_bf16 v[120:123], v[140:143], v[164:167], v[120:123]
	v_mfma_f32_16x16x32_bf16 v[104:107], v[140:143], v[172:175], v[104:107]
	v_mfma_f32_16x16x32_bf16 v[100:103], v[132:135], v[172:175], v[100:103]
	v_mfma_f32_16x16x32_bf16 v[76:79], v[132:135], v[180:183], v[76:79]
	v_mfma_f32_16x16x32_bf16 v[80:83], v[140:143], v[180:183], v[80:83]
	v_mfma_f32_16x16x32_bf16 v[48:51], v[140:143], v[236:239], v[48:51]
	v_mfma_f32_16x16x32_bf16 v[44:47], v[132:135], v[236:239], v[44:47]
	v_mfma_f32_16x16x32_bf16 v[116:119], v[136:139], v[168:171], v[116:119]
	v_mfma_f32_16x16x32_bf16 v[120:123], v[144:147], v[168:171], v[120:123]
	v_mfma_f32_16x16x32_bf16 v[104:107], v[144:147], v[176:179], v[104:107]
	v_mfma_f32_16x16x32_bf16 v[100:103], v[136:139], v[176:179], v[100:103]
	v_mfma_f32_16x16x32_bf16 v[76:79], v[136:139], v[184:187], v[76:79]
	v_mfma_f32_16x16x32_bf16 v[80:83], v[144:147], v[184:187], v[80:83]
	v_mfma_f32_16x16x32_bf16 v[48:51], v[144:147], v[240:243], v[48:51]
	v_mfma_f32_16x16x32_bf16 v[44:47], v[136:139], v[240:243], v[44:47]
	v_mfma_f32_16x16x32_bf16 v[124:127], v[148:151], v[164:167], v[124:127]
	v_mfma_f32_16x16x32_bf16 v[128:131], v[156:159], v[164:167], v[128:131]
	v_mfma_f32_16x16x32_bf16 v[112:115], v[156:159], v[172:175], v[112:115]
	v_mfma_f32_16x16x32_bf16 v[108:111], v[148:151], v[172:175], v[108:111]
	v_mfma_f32_16x16x32_bf16 v[92:95], v[148:151], v[180:183], v[92:95]
	v_mfma_f32_16x16x32_bf16 v[96:99], v[156:159], v[180:183], v[96:99]
	v_mfma_f32_16x16x32_bf16 v[72:75], v[156:159], v[236:239], v[72:75]
	v_mfma_f32_16x16x32_bf16 v[68:71], v[148:151], v[236:239], v[68:71]
	v_mfma_f32_16x16x32_bf16 v[124:127], v[152:155], v[168:171], v[124:127]
	v_mfma_f32_16x16x32_bf16 v[128:131], v[160:163], v[168:171], v[128:131]
	v_mfma_f32_16x16x32_bf16 v[112:115], v[160:163], v[176:179], v[112:115]
	v_mfma_f32_16x16x32_bf16 v[108:111], v[152:155], v[176:179], v[108:111]
	v_mfma_f32_16x16x32_bf16 v[92:95], v[152:155], v[184:187], v[92:95]
	v_mfma_f32_16x16x32_bf16 v[96:99], v[160:163], v[184:187], v[96:99]
	v_mfma_f32_16x16x32_bf16 v[72:75], v[160:163], v[240:243], v[72:75]
	v_mfma_f32_16x16x32_bf16 v[68:71], v[152:155], v[240:243], v[68:71]
	s_barrier
	s_setprio 0
	s_add_i32 s65, s65, s41
	v_lshl_add_u64 v[208:209], s[62:63], 0, v[192:193]
	s_mov_b32 m0, s65
	ds_read_b128 v[164:167], v235 offset:16384
	ds_read_b128 v[168:171], v235 offset:17408
	ds_read_b128 v[172:175], v235 offset:18432
	ds_read_b128 v[176:179], v235 offset:19456
	ds_read_b128 v[180:183], v235 offset:20480
	ds_read_b128 v[184:187], v235 offset:21504
	ds_read_b128 v[236:239], v235 offset:22528
	ds_read_b128 v[240:243], v235 offset:23552
	global_load_lds_dwordx4 v[208:209], off
	s_add_i32 m0, s65, 0x2000
	v_lshl_add_u64 v[244:245], s[62:63], 0, v[196:197]
	s_add_u32 s62, s62, s16
	s_addc_u32 s63, s63, 0
	s_add_i32 s64, s64, s41
	global_load_lds_dwordx4 v[244:245], off
	v_lshl_add_u64 v[246:247], s[62:63], 0, v[192:193]
	s_mov_b32 m0, s64
	v_lshl_add_u64 v[248:249], s[62:63], 0, v[196:197]
	global_load_lds_dwordx4 v[246:247], off
	s_add_i32 m0, s64, 0x2000
	v_lshl_add_u64 v[250:251], s[34:35], 0, v[190:191]
	global_load_lds_dwordx4 v[248:249], off
	s_mov_b32 m0, s43
	v_lshl_add_u64 v[212:213], s[34:35], 0, v[194:195]
	global_load_lds_dwordx4 v[250:251], off
	s_mov_b32 m0, s44
	s_nop 0
	global_load_lds_dwordx4 v[212:213], off
	s_waitcnt vmcnt(8)
	s_waitcnt lgkmcnt(0)
	s_setprio 1
	s_barrier
; #define PG8_STAGE(bufoff, gbase, voff) do { _Pragma("unroll") for (int _i = 0; _i < 2; ++_i) \
;         __builtin_amdgcn_global_load_lds((const unsigned*)((const char*)(gbase) + (voff)[_i]), (PG8_LAS unsigned*)(lds + (bufoff) + ldsw + _i * 8192), 16, 0, 0); } while (0)
; #define PG8_LDA(dst, b, h) do { _Pragma("unroll") for (int m = 0; m < 4; ++m) _Pragma("unroll") for (int k = 0; k < 2; ++k) dst[m][k] = *(const PG8_LAS bf16x8*)(lds + PG8_SA(b, h) + aoff + m * 2048 + k * 1024); } while (0)
; #define PG8_LDB(dst, b, h) do { _Pragma("unroll") for (int n = 0; n < 2; ++n) _Pragma("unroll") for (int k = 0; k < 2; ++k) dst[n][k] = *(const PG8_LAS bf16x8*)(lds + PG8_SB(b, h) + boff + n * 2048 + k * 1024); } while (0)
; #define PG8_MMA(ai, bj, At, Bt) do { __builtin_amdgcn_s_setprio(1); _Pragma("unroll") for (int m = 0; m < 4; ++m) _Pragma("unroll") for (int n = 0; n < 2; ++n) _Pragma("unroll") for (int k = 0; k < 2; ++k) \
;         acc[ai][bj][m][n] = __builtin_amdgcn_mfma_f32_16x16x32_bf16(Bt[n][k], At[m][k], acc[ai][bj][m][n], 0, 0, 0); __builtin_amdgcn_s_setprio(0); } while (0)
; #define PG8_WAIT_V(n) asm volatile("s_waitcnt vmcnt(" #n ")" ::: "memory")
; template <class Epi, class Sched, bool ALIGN_EPI = false, bool SP2 = false>
; __device__ __forceinline__ void gemm_phase(PG8_LAS unsigned char* lds, const Gemm g, const Sched& S, const Epi& E) {
;     ...
;             PG8_LDB(B0, 0, 0); PG8_LDB(B1, 0, 1); PG8_SCHED; PG8_LDA(At, 0, 0); PG8_STAGE(PG8_SA(1, 1), a1 + hstep, voffA);
;             PG8_WAIT_V(8); PG8_WAIT_L(0); PG8_BAR; PG8_MMA(0, 0, At, B0); PG8_MMA(0, 1, At, B1); PG8_BAR; PG8_SCHED;
;             PG8_LDA(At, 0, 1); PG8_STAGE(PG8_SB(0, 0), b2, voffB); PG8_STAGE(PG8_SB(0, 1), b2 + hstep, voffB); PG8_STAGE(PG8_SA(0, 0), a2, voffA);
;             PG8_WAIT_V(8); PG8_WAIT_L(0); PG8_BAR; PG8_MMA(1, 0, At, B0); PG8_MMA(1, 1, At, B1); PG8_BAR; PG8_SCHED;
;             PG8_LDB(B0, 1, 0); PG8_LDB(B1, 1, 1); PG8_SCHED; PG8_LDA(At, 1, 0); PG8_STAGE(PG8_SA(0, 1), a2 + hstep, voffA);
;             PG8_WAIT_V(8); PG8_WAIT_L(0); PG8_BAR; PG8_MMA(0, 0, At, B0); PG8_MMA(0, 1, At, B1); PG8_BAR; PG8_SCHED;
;             PG8_LDA(At, 1, 1); PG8_STAGE(PG8_SB(1, 0), b3, voffB); PG8_STAGE(PG8_SB(1, 1), b3 + hstep, voffB); PG8_STAGE(PG8_SA(1, 0), a3, voffA);
;             PG8_WAIT_V(8); PG8_WAIT_L(0); PG8_BAR; PG8_MMA(1, 0, At, B0); PG8_MMA(1, 1, At, B1); PG8_BAR; PG8_SCHED;
	v_mfma_f32_16x16x32_bf16 v[60:63], v[132:135], v[164:167], v[60:63]
	v_mfma_f32_16x16x32_bf16 v[64:67], v[140:143], v[164:167], v[64:67]
	v_mfma_f32_16x16x32_bf16 v[40:43], v[140:143], v[172:175], v[40:43]
	v_mfma_f32_16x16x32_bf16 v[36:39], v[132:135], v[172:175], v[36:39]
	v_mfma_f32_16x16x32_bf16 v[20:23], v[132:135], v[180:183], v[20:23]
	v_mfma_f32_16x16x32_bf16 v[24:27], v[140:143], v[180:183], v[24:27]
	v_mfma_f32_16x16x32_bf16 v[2:5], v[132:135], v[236:239], v[4:7]
	v_mfma_f32_16x16x32_bf16 v[6:9], v[140:143], v[236:239], v[8:11]
	v_mfma_f32_16x16x32_bf16 v[60:63], v[136:139], v[168:171], v[60:63]
	v_mfma_f32_16x16x32_bf16 v[64:67], v[144:147], v[168:171], v[64:67]
	v_mfma_f32_16x16x32_bf16 v[40:43], v[144:147], v[176:179], v[40:43]
	v_mfma_f32_16x16x32_bf16 v[36:39], v[136:139], v[176:179], v[36:39]
	v_mfma_f32_16x16x32_bf16 v[20:23], v[136:139], v[184:187], v[20:23]
	v_mfma_f32_16x16x32_bf16 v[24:27], v[144:147], v[184:187], v[24:27]
	v_mfma_f32_16x16x32_bf16 v[2:5], v[136:139], v[240:243], v[2:5]
	v_mfma_f32_16x16x32_bf16 v[8:11], v[144:147], v[240:243], v[6:9]
	v_mfma_f32_16x16x32_bf16 v[84:87], v[148:151], v[164:167], v[84:87]
	v_mfma_f32_16x16x32_bf16 v[88:91], v[156:159], v[164:167], v[88:91]
	v_mfma_f32_16x16x32_bf16 v[56:59], v[156:159], v[172:175], v[56:59]
	v_mfma_f32_16x16x32_bf16 v[52:55], v[148:151], v[172:175], v[52:55]
	v_mfma_f32_16x16x32_bf16 v[28:31], v[148:151], v[180:183], v[28:31]
	v_mfma_f32_16x16x32_bf16 v[32:35], v[156:159], v[180:183], v[32:35]
	v_mfma_f32_16x16x32_bf16 v[16:19], v[156:159], v[236:239], v[16:19]
	v_mfma_f32_16x16x32_bf16 v[12:15], v[148:151], v[236:239], v[12:15]
	v_mfma_f32_16x16x32_bf16 v[84:87], v[152:155], v[168:171], v[84:87]
	v_mfma_f32_16x16x32_bf16 v[88:91], v[160:163], v[168:171], v[88:91]
	v_mfma_f32_16x16x32_bf16 v[56:59], v[160:163], v[176:179], v[56:59]
	v_mfma_f32_16x16x32_bf16 v[52:55], v[152:155], v[176:179], v[52:55]
	v_mfma_f32_16x16x32_bf16 v[28:31], v[152:155], v[184:187], v[28:31]
	v_mfma_f32_16x16x32_bf16 v[32:35], v[160:163], v[184:187], v[32:35]
	v_mfma_f32_16x16x32_bf16 v[16:19], v[160:163], v[240:243], v[16:19]
	v_mfma_f32_16x16x32_bf16 v[12:15], v[152:155], v[240:243], v[12:15]
	s_barrier
	s_setprio 0
	s_add_i32 s62, 0, 0x18000
	v_add_u32_e32 v0, s62, v188
	s_add_i32 s63, 0, 0x1c000
	ds_read_b128 v[132:135], v0
	ds_read_b128 v[136:139], v0 offset:1024
	ds_read_b128 v[140:143], v0 offset:2048
	ds_read_b128 v[144:147], v0 offset:3072
	v_add_u32_e32 v0, s63, v188
	ds_read_b128 v[148:151], v0
	ds_read_b128 v[152:155], v0 offset:1024
	ds_read_b128 v[156:159], v0 offset:2048
	ds_read_b128 v[160:163], v0 offset:3072
	s_add_u32 s34, s34, s16
	s_addc_u32 s35, s35, 0
	s_mov_b32 m0, s45
	v_lshl_add_u64 v[6:7], s[34:35], 0, v[190:191]
	ds_read_b128 v[164:167], v235 offset:32768
	ds_read_b128 v[168:171], v235 offset:33792
	ds_read_b128 v[172:175], v235 offset:34816
	ds_read_b128 v[176:179], v235 offset:35840
	ds_read_b128 v[180:183], v235 offset:36864
	ds_read_b128 v[184:187], v235 offset:37888
	ds_read_b128 v[236:239], v235 offset:38912
	ds_read_b128 v[240:243], v235 offset:39936
	global_load_lds_dwordx4 v[6:7], off
	v_lshl_add_u64 v[6:7], s[34:35], 0, v[194:195]
	s_mov_b32 m0, s46
	s_nop 0
	global_load_lds_dwordx4 v[6:7], off
	s_waitcnt vmcnt(8)
	s_waitcnt lgkmcnt(0)
	s_setprio 1
	s_barrier
	v_mfma_f32_16x16x32_bf16 v[116:119], v[132:135], v[164:167], v[116:119]
	v_mfma_f32_16x16x32_bf16 v[120:123], v[140:143], v[164:167], v[120:123]
	v_mfma_f32_16x16x32_bf16 v[104:107], v[140:143], v[172:175], v[104:107]
	v_mfma_f32_16x16x32_bf16 v[100:103], v[132:135], v[172:175], v[100:103]
	v_mfma_f32_16x16x32_bf16 v[76:79], v[132:135], v[180:183], v[76:79]
	v_mfma_f32_16x16x32_bf16 v[80:83], v[140:143], v[180:183], v[80:83]
	v_mfma_f32_16x16x32_bf16 v[48:51], v[140:143], v[236:239], v[48:51]
	v_mfma_f32_16x16x32_bf16 v[44:47], v[132:135], v[236:239], v[44:47]
	v_mfma_f32_16x16x32_bf16 v[116:119], v[136:139], v[168:171], v[116:119]
	v_mfma_f32_16x16x32_bf16 v[120:123], v[144:147], v[168:171], v[120:123]
	v_mfma_f32_16x16x32_bf16 v[104:107], v[144:147], v[176:179], v[104:107]
	v_mfma_f32_16x16x32_bf16 v[100:103], v[136:139], v[176:179], v[100:103]
	v_mfma_f32_16x16x32_bf16 v[76:79], v[136:139], v[184:187], v[76:79]
	v_mfma_f32_16x16x32_bf16 v[80:83], v[144:147], v[184:187], v[80:83]
	v_mfma_f32_16x16x32_bf16 v[48:51], v[144:147], v[240:243], v[48:51]
	v_mfma_f32_16x16x32_bf16 v[44:47], v[136:139], v[240:243], v[44:47]
	v_mfma_f32_16x16x32_bf16 v[124:127], v[148:151], v[164:167], v[124:127]
	v_mfma_f32_16x16x32_bf16 v[128:131], v[156:159], v[164:167], v[128:131]
	v_mfma_f32_16x16x32_bf16 v[112:115], v[156:159], v[172:175], v[112:115]
	v_mfma_f32_16x16x32_bf16 v[108:111], v[148:151], v[172:175], v[108:111]
	v_mfma_f32_16x16x32_bf16 v[92:95], v[148:151], v[180:183], v[92:95]
	v_mfma_f32_16x16x32_bf16 v[96:99], v[156:159], v[180:183], v[96:99]
	v_mfma_f32_16x16x32_bf16 v[72:75], v[156:159], v[236:239], v[72:75]
	v_mfma_f32_16x16x32_bf16 v[68:71], v[148:151], v[236:239], v[68:71]
	v_mfma_f32_16x16x32_bf16 v[124:127], v[152:155], v[168:171], v[124:127]
	v_mfma_f32_16x16x32_bf16 v[128:131], v[160:163], v[168:171], v[128:131]
	v_mfma_f32_16x16x32_bf16 v[112:115], v[160:163], v[176:179], v[112:115]
	v_mfma_f32_16x16x32_bf16 v[108:111], v[152:155], v[176:179], v[108:111]
	v_mfma_f32_16x16x32_bf16 v[92:95], v[152:155], v[184:187], v[92:95]
	v_mfma_f32_16x16x32_bf16 v[96:99], v[160:163], v[184:187], v[96:99]
	v_mfma_f32_16x16x32_bf16 v[72:75], v[160:163], v[240:243], v[72:75]
	v_mfma_f32_16x16x32_bf16 v[68:71], v[152:155], v[240:243], v[68:71]
	s_barrier
; #define PG8_STAGE(bufoff, gbase, voff) do { _Pragma("unroll") for (int _i = 0; _i < 2; ++_i) \
;         __builtin_amdgcn_global_load_lds((const unsigned*)((const char*)(gbase) + (voff)[_i]), (PG8_LAS unsigned*)(lds + (bufoff) + ldsw + _i * 8192), 16, 0, 0); } while (0)
; #define PG8_LDA(dst, b, h) do { _Pragma("unroll") for (int m = 0; m < 4; ++m) _Pragma("unroll") for (int k = 0; k < 2; ++k) dst[m][k] = *(const PG8_LAS bf16x8*)(lds + PG8_SA(b, h) + aoff + m * 2048 + k * 1024); } while (0)
; #define PG8_LDB(dst, b, h) do { _Pragma("unroll") for (int n = 0; n < 2; ++n) _Pragma("unroll") for (int k = 0; k < 2; ++k) dst[n][k] = *(const PG8_LAS bf16x8*)(lds + PG8_SB(b, h) + boff + n * 2048 + k * 1024); } while (0)
; #define PG8_MMA(ai, bj, At, Bt) do { __builtin_amdgcn_s_setprio(1); _Pragma("unroll") for (int m = 0; m < 4; ++m) _Pragma("unroll") for (int n = 0; n < 2; ++n) _Pragma("unroll") for (int k = 0; k < 2; ++k) \
;         acc[ai][bj][m][n] = __builtin_amdgcn_mfma_f32_16x16x32_bf16(Bt[n][k], At[m][k], acc[ai][bj][m][n], 0, 0, 0); __builtin_amdgcn_s_setprio(0); } while (0)
; #define PG8_WAIT_V(n) asm volatile("s_waitcnt vmcnt(" #n ")" ::: "memory")
; #define PG8_WAIT_L(n) asm volatile("s_waitcnt lgkmcnt(" #n ")" ::: "memory")
; #define PG8_BAR __builtin_amdgcn_s_barrier()
; #define PG8_SCHED __builtin_amdgcn_sched_barrier(0)
; template <class Epi, class Sched, bool ALIGN_EPI = false, bool SP2 = false>
; __device__ __forceinline__ void gemm_phase(PG8_LAS unsigned char* lds, const Gemm g, const Sched& S, const Epi& E) {
;     ...
;             PG8_LDB(B0, 1, 0); PG8_LDB(B1, 1, 1); PG8_SCHED; PG8_LDA(At, 1, 0); PG8_STAGE(PG8_SA(0, 1), a2 + hstep, voffA);
;             PG8_WAIT_V(8); PG8_WAIT_L(0); PG8_BAR; PG8_MMA(0, 0, At, B0); PG8_MMA(0, 1, At, B1); PG8_BAR; PG8_SCHED;
;             PG8_LDA(At, 1, 1); PG8_STAGE(PG8_SB(1, 0), b3, voffB); PG8_STAGE(PG8_SB(1, 1), b3 + hstep, voffB); PG8_STAGE(PG8_SA(1, 0), a3, voffA);
;             PG8_WAIT_V(8); PG8_WAIT_L(0); PG8_BAR; PG8_MMA(1, 0, At, B0); PG8_MMA(1, 1, At, B1); PG8_BAR; PG8_SCHED;
	s_setprio 0
	s_add_i32 s34, s62, s41
	v_lshl_add_u64 v[6:7], v[208:209], 0, s[92:93]
	s_mov_b32 m0, s34
	ds_read_b128 v[164:167], v235 offset:49152
	ds_read_b128 v[168:171], v235 offset:50176
	ds_read_b128 v[172:175], v235 offset:51200
	ds_read_b128 v[176:179], v235 offset:52224
	ds_read_b128 v[180:183], v235 offset:53248
	ds_read_b128 v[184:187], v235 offset:54272
	ds_read_b128 v[236:239], v235 offset:55296
	ds_read_b128 v[240:243], v235 offset:56320
	global_load_lds_dwordx4 v[6:7], off
	v_lshl_add_u64 v[6:7], v[244:245], 0, s[92:93]
	s_add_i32 m0, s34, 0x2000
	s_add_i32 s34, s63, s41
	global_load_lds_dwordx4 v[6:7], off
	v_lshl_add_u64 v[6:7], v[246:247], 0, s[92:93]
	s_mov_b32 m0, s34
	s_nop 0
	global_load_lds_dwordx4 v[6:7], off
	v_lshl_add_u64 v[6:7], v[248:249], 0, s[92:93]
	s_add_i32 m0, s34, 0x2000
	s_nop 0
	global_load_lds_dwordx4 v[6:7], off
	v_lshl_add_u64 v[6:7], v[250:251], 0, s[92:93]
	s_mov_b32 m0, s51
	s_nop 0
	global_load_lds_dwordx4 v[6:7], off
	v_lshl_add_u64 v[6:7], v[212:213], 0, s[92:93]
	s_mov_b32 m0, s52
	s_nop 0
	global_load_lds_dwordx4 v[6:7], off
	s_waitcnt vmcnt(8)
	s_waitcnt lgkmcnt(0)
	s_setprio 1
	s_barrier
	v_mfma_f32_16x16x32_bf16 v[60:63], v[132:135], v[164:167], v[60:63]
	v_mfma_f32_16x16x32_bf16 v[64:67], v[140:143], v[164:167], v[64:67]
	v_mfma_f32_16x16x32_bf16 v[40:43], v[140:143], v[172:175], v[40:43]
	v_mfma_f32_16x16x32_bf16 v[36:39], v[132:135], v[172:175], v[36:39]
	v_mfma_f32_16x16x32_bf16 v[20:23], v[132:135], v[180:183], v[20:23]
	v_mfma_f32_16x16x32_bf16 v[24:27], v[140:143], v[180:183], v[24:27]
	v_mfma_f32_16x16x32_bf16 v[8:11], v[140:143], v[236:239], v[8:11]
	v_mfma_f32_16x16x32_bf16 v[2:5], v[132:135], v[236:239], v[2:5]
	v_mfma_f32_16x16x32_bf16 v[60:63], v[136:139], v[168:171], v[60:63]
	v_mfma_f32_16x16x32_bf16 v[64:67], v[144:147], v[168:171], v[64:67]
	v_mfma_f32_16x16x32_bf16 v[40:43], v[144:147], v[176:179], v[40:43]
	v_mfma_f32_16x16x32_bf16 v[36:39], v[136:139], v[176:179], v[36:39]
	v_mfma_f32_16x16x32_bf16 v[20:23], v[136:139], v[184:187], v[20:23]
	v_mfma_f32_16x16x32_bf16 v[24:27], v[144:147], v[184:187], v[24:27]
	v_mfma_f32_16x16x32_bf16 v[4:7], v[136:139], v[240:243], v[2:5]
	v_mfma_f32_16x16x32_bf16 v[8:11], v[144:147], v[240:243], v[8:11]
	v_mfma_f32_16x16x32_bf16 v[84:87], v[148:151], v[164:167], v[84:87]
	v_mfma_f32_16x16x32_bf16 v[88:91], v[156:159], v[164:167], v[88:91]
	v_mfma_f32_16x16x32_bf16 v[56:59], v[156:159], v[172:175], v[56:59]
	v_mfma_f32_16x16x32_bf16 v[52:55], v[148:151], v[172:175], v[52:55]
	v_mfma_f32_16x16x32_bf16 v[28:31], v[148:151], v[180:183], v[28:31]
	v_mfma_f32_16x16x32_bf16 v[32:35], v[156:159], v[180:183], v[32:35]
	v_mfma_f32_16x16x32_bf16 v[16:19], v[156:159], v[236:239], v[16:19]
	v_mfma_f32_16x16x32_bf16 v[12:15], v[148:151], v[236:239], v[12:15]
	v_mfma_f32_16x16x32_bf16 v[84:87], v[152:155], v[168:171], v[84:87]
	v_mfma_f32_16x16x32_bf16 v[88:91], v[160:163], v[168:171], v[88:91]
	v_mfma_f32_16x16x32_bf16 v[56:59], v[160:163], v[176:179], v[56:59]
	v_mfma_f32_16x16x32_bf16 v[52:55], v[152:155], v[176:179], v[52:55]
	v_mfma_f32_16x16x32_bf16 v[28:31], v[152:155], v[184:187], v[28:31]
	v_mfma_f32_16x16x32_bf16 v[32:35], v[160:163], v[184:187], v[32:35]
	v_mfma_f32_16x16x32_bf16 v[16:19], v[160:163], v[240:243], v[16:19]
	v_mfma_f32_16x16x32_bf16 v[12:15], v[152:155], v[240:243], v[12:15]
	s_barrier
	s_setprio 0
	s_add_u32 s30, s30, 0x100
	s_addc_u32 s31, s31, 0
	s_cmp_ge_u32 s2, s47
	s_cbranch_scc1 .LBB0_58
	s_mov_b32 s34, s2
	s_branch .LBB0_54
